# hgrn_b state scan: the 16 loads of each 8-step group issued ahead of the dependent FMA chain with counted vmcnt; no per-step store waits
# speedup vs baseline: 1.0140x; 1.0008x over previous
.LBB0_264:
	v_lshl_add_u64 v[10:11], s[20:21], 0, v[4:5]
	v_lshl_add_u64 v[6:7], s[20:21], 0, v[0:1]
	v_add_u32_e32 v8, s8, v14
	v_ashrrev_i32_e32 v9, 31, v8
	v_lshl_add_u64 v[8:9], v[8:9], 2, s[38:39]
	s_mov_b32 s22, 0xc400000
	s_mov_b32 s23, 0
	global_load_dword v60, v[8:9], off
	v_lshl_add_u64 v[16:17], v[6:7], 0, s[22:23]
	global_load_dword v61, v[16:17], off
	s_add_u32 s22, s22, 0x4000
	global_load_dword v62, v[8:9], off offset:256
	v_lshl_add_u64 v[16:17], v[6:7], 0, s[22:23]
	global_load_dword v63, v[16:17], off
	s_add_u32 s22, s22, 0x4000
	global_load_dword v64, v[8:9], off offset:512
	v_lshl_add_u64 v[16:17], v[6:7], 0, s[22:23]
	global_load_dword v65, v[16:17], off
	s_add_u32 s22, s22, 0x4000
	global_load_dword v66, v[8:9], off offset:768
	v_lshl_add_u64 v[16:17], v[6:7], 0, s[22:23]
	global_load_dword v67, v[16:17], off
	s_add_u32 s22, s22, 0x4000
	global_load_dword v68, v[8:9], off offset:1024
	v_lshl_add_u64 v[16:17], v[6:7], 0, s[22:23]
	global_load_dword v69, v[16:17], off
	s_add_u32 s22, s22, 0x4000
	global_load_dword v70, v[8:9], off offset:1280
	v_lshl_add_u64 v[16:17], v[6:7], 0, s[22:23]
	global_load_dword v71, v[16:17], off
	s_add_u32 s22, s22, 0x4000
	global_load_dword v72, v[8:9], off offset:1536
	v_lshl_add_u64 v[16:17], v[6:7], 0, s[22:23]
	global_load_dword v73, v[16:17], off
	s_add_u32 s22, s22, 0x4000
	global_load_dword v74, v[8:9], off offset:1792
	v_lshl_add_u64 v[16:17], v[6:7], 0, s[22:23]
	global_load_dword v75, v[16:17], off
	s_mov_b32 s22, 0x1c000000
	v_cvt_pk_bf16_f32 v18, v15, v2
	v_lshl_add_u64 v[16:17], v[10:11], 0, s[22:23]
	global_store_short v[16:17], v18, off
	s_add_u32 s22, s22, 0x2000
	s_waitcnt vmcnt(15)
	v_fmac_f32_e32 v61, v15, v60
	v_cvt_pk_bf16_f32 v18, v61, v2
	v_lshl_add_u64 v[16:17], v[10:11], 0, s[22:23]
	global_store_short v[16:17], v18, off
	s_add_u32 s22, s22, 0x2000
	s_waitcnt vmcnt(14)
	v_fmac_f32_e32 v63, v61, v62
	v_cvt_pk_bf16_f32 v18, v63, v2
	v_lshl_add_u64 v[16:17], v[10:11], 0, s[22:23]
	global_store_short v[16:17], v18, off
	s_add_u32 s22, s22, 0x2000
	s_waitcnt vmcnt(13)
	v_fmac_f32_e32 v65, v63, v64
	v_cvt_pk_bf16_f32 v18, v65, v2
	v_lshl_add_u64 v[16:17], v[10:11], 0, s[22:23]
	global_store_short v[16:17], v18, off
	s_add_u32 s22, s22, 0x2000
	s_waitcnt vmcnt(12)
	v_fmac_f32_e32 v67, v65, v66
	v_cvt_pk_bf16_f32 v18, v67, v2
	v_lshl_add_u64 v[16:17], v[10:11], 0, s[22:23]
	global_store_short v[16:17], v18, off
	s_add_u32 s22, s22, 0x2000
	s_waitcnt vmcnt(11)
	v_fmac_f32_e32 v69, v67, v68
	v_cvt_pk_bf16_f32 v18, v69, v2
	v_lshl_add_u64 v[16:17], v[10:11], 0, s[22:23]
	global_store_short v[16:17], v18, off
	s_add_u32 s22, s22, 0x2000
	s_waitcnt vmcnt(10)
	v_fmac_f32_e32 v71, v69, v70
	v_cvt_pk_bf16_f32 v18, v71, v2
	v_lshl_add_u64 v[16:17], v[10:11], 0, s[22:23]
	global_store_short v[16:17], v18, off
	s_add_u32 s22, s22, 0x2000
	s_waitcnt vmcnt(9)
	v_fmac_f32_e32 v73, v71, v72
	v_cvt_pk_bf16_f32 v18, v73, v2
	v_lshl_add_u64 v[16:17], v[10:11], 0, s[22:23]
	global_store_short v[16:17], v18, off
	s_waitcnt vmcnt(8)
	v_fmac_f32_e32 v75, v73, v74
	v_mov_b32_e32 v15, v75
	s_addk_i32 s8, 0x200
	s_mov_b64 s[22:23], 0x20000
	v_lshl_add_u64 v[0:1], v[0:1], 0, s[22:23]
	s_mov_b64 s[22:23], 0x10000
	v_lshl_add_u64 v[4:5], v[4:5], 0, s[22:23]
	s_cmpk_eq_i32 s8, 0x1000
	s_cbranch_scc0 .LBB0_264
	v_add_u32_e32 v3, s83, v3
	s_movk_i32 s8, 0x3fff
	v_cmp_lt_i32_e32 vcc, s8, v3
	s_or_b64 s[40:41], vcc, s[40:41]
	v_add_u16_e32 v13, s83, v13
	s_andn2_b64 exec, exec, s[40:41]
	s_cbranch_execnz .LBB0_263
